# strategy 7.1 (de-waterfall a provably uniform buffer descriptor): the 20 waterfall loops around the prep unit's buffer stores no longer compare/mask (descriptor v[94:95],v[174:175] is wave-uniform); s
# baseline (speedup 1.0000x reference)
; __device__ __forceinline__ unsigned pack2(float lo, float hi) { return pg8::cvt_pk_bf16(lo, hi); }
; __device__ void prep_unit(unsigned char* lds, int bh, int n, const bf16_t* pc, const float* scal, const float* convw  , float alog, float dtb, unsigned char* unit, float* egl, unsigned* flag, unsigned fval) {
;     ...
; #pragma unroll
;         for (int it = 0; it < 4; ++it) {
;             const int q = u + 256 * it, f = q >> 6, L = q & 63, mt = f >> 2, ks = f & 3, quad = L >> 4, r = L & 15, i_ = 16 * mt + r;
;             const float eg = __expf(gc[i_]) * rq[i_]; float v[8];
; #pragma unroll
;             for (int jj = 0; jj < 8; ++jj) { const int kd = 32 * ks + 16 * (jj >> 2) + 4 * quad + (jj & 3); v[jj] = qT[kd * 68 + i_] * eg; }
;             u32x4 w; w.x = pack2(v[0], v[1]); w.y = pack2(v[2], v[3]); w.z = pack2(v[4], v[5]); w.w = pack2(v[6], v[7]);
;             __builtin_amdgcn_raw_buffer_store_b128(w, ur, 16384 + q * 16, 0, 16);
;         }
; #pragma unroll
;         for (int it = 0; it < 4; ++it) {
;             const int q = u + 256 * it, f = q >> 6, L = q & 63, mt = f >> 1, ks = f & 1, quad = L >> 4, r = L & 15, kd = 16 * mt + r;
;             float v[8];
; #pragma unroll
;             for (int hh = 0; hh < 2; ++hh) { const int c0 = 32 * ks + 16 * hh + 4 * quad; const f32x4 kk = *(const f32x4*)(kT + kd * 68 + c0), gg = *(const f32x4*)(gc + c0), rr = *(const f32x4*)(rk + c0);
; #pragma unroll
;                 for (int j = 0; j < 4; ++j) v[hh * 4 + j] = kk[j] * rr[j] * __expf(glast - gg[j]); }
;             u32x4 w; w.x = pack2(v[0], v[1]); w.y = pack2(v[2], v[3]); w.z = pack2(v[4], v[5]); w.w = pack2(v[6], v[7]);
;             __builtin_amdgcn_raw_buffer_store_b128(w, ur, 32768 + q * 16, 0, 16);
.LBB0_383:
	v_readfirstlane_b32 s8, v94
	v_readfirstlane_b32 s9, v95
	v_readfirstlane_b32 s10, v174
	v_readfirstlane_b32 s11, v175
	s_nop 4
	s_nop 0
	s_nop 0
	s_nop 0
	s_nop 0
	s_mov_b64 s[0:1], exec
	buffer_store_dwordx4 v[2:5], v8, s[8:11], 0 offen sc1
	s_xor_b64 exec, exec, s[0:1]
	s_cbranch_execnz .LBB0_383
	s_mov_b64 exec, s[14:15]
	v_lshrrev_b32_e32 v2, 4, v156
	s_mov_b32 s0, 0x7fffff0
	v_and_or_b32 v2, v2, s0, v108
	v_lshlrev_b32_e32 v2, 2, v2
	v_add_u32_e32 v3, s17, v2
	ds_read_b32 v4, v3
	v_add_u32_e32 v3, s16, v2
	v_add3_u32 v10, 0, v2, v7
	ds_read_b32 v12, v3
	ds_read2_b32 v[2:3], v10 offset1:68
	v_add_u32_e32 v8, 0x1000, v10
	s_waitcnt lgkmcnt(2)
	v_mul_f32_e32 v4, 0x3fb8aa3b, v4
	v_exp_f32_e32 v13, v4
	ds_read2_b32 v[4:5], v10 offset0:136 offset1:204
	v_add_u32_e32 v10, 0x1200, v10
	ds_read2_b32 v[8:9], v8 offset0:64 offset1:132
	ds_read2_b32 v[10:11], v10 offset0:72 offset1:140
	s_waitcnt lgkmcnt(4)
	v_mul_f32_e32 v12, v12, v13
	s_waitcnt lgkmcnt(3)
	v_pk_mul_f32 v[2:3], v[2:3], v[12:13] op_sel_hi:[1,0]
	s_waitcnt lgkmcnt(2)
	v_pk_mul_f32 v[4:5], v[12:13], v[4:5] op_sel_hi:[0,1]
	s_waitcnt lgkmcnt(1)
	v_pk_mul_f32 v[8:9], v[12:13], v[8:9] op_sel_hi:[0,1]
	s_waitcnt lgkmcnt(0)
	v_pk_mul_f32 v[10:11], v[12:13], v[10:11] op_sel_hi:[0,1]
	v_lshlrev_b32_e32 v26, 4, v156
	v_cvt_pk_bf16_f32 v2, v2, v3
	v_cvt_pk_bf16_f32 v3, v4, v5
	v_cvt_pk_bf16_f32 v4, v8, v9
	v_cvt_pk_bf16_f32 v5, v10, v11
	v_add_u32_e32 v8, 0x4000, v26
	s_mov_b64 s[14:15], exec
.LBB0_385:
	v_readfirstlane_b32 s8, v94
	v_readfirstlane_b32 s9, v95
	v_readfirstlane_b32 s10, v174
	v_readfirstlane_b32 s11, v175
	s_nop 4
	s_nop 0
	s_nop 0
	s_nop 0
	s_nop 0
	s_mov_b64 s[0:1], exec
	buffer_store_dwordx4 v[2:5], v8, s[8:11], 0 offen sc1
	s_xor_b64 exec, exec, s[0:1]
	s_cbranch_execnz .LBB0_385
	s_mov_b64 exec, s[14:15]
	v_add_u32_e32 v27, 0x100, v156
	v_lshrrev_b32_e32 v2, 4, v27
	s_mov_b32 s0, 0x7fffff0
	v_and_or_b32 v2, v2, s0, v108
	v_lshlrev_b32_e32 v2, 2, v2
	v_add_u32_e32 v3, s17, v2
	ds_read_b32 v4, v3
	v_add_u32_e32 v3, s16, v2
	v_add3_u32 v10, 0, v2, v7
	ds_read_b32 v12, v3
	ds_read2_b32 v[2:3], v10 offset1:68
	v_add_u32_e32 v8, 0x1000, v10
	s_waitcnt lgkmcnt(2)
	v_mul_f32_e32 v4, 0x3fb8aa3b, v4
	v_exp_f32_e32 v13, v4
	ds_read2_b32 v[4:5], v10 offset0:136 offset1:204
	v_add_u32_e32 v10, 0x1200, v10
	ds_read2_b32 v[8:9], v8 offset0:64 offset1:132
	ds_read2_b32 v[10:11], v10 offset0:72 offset1:140
	s_waitcnt lgkmcnt(4)
	v_mul_f32_e32 v12, v12, v13
	s_waitcnt lgkmcnt(3)
	v_pk_mul_f32 v[2:3], v[2:3], v[12:13] op_sel_hi:[1,0]
	s_waitcnt lgkmcnt(2)
	v_pk_mul_f32 v[4:5], v[12:13], v[4:5] op_sel_hi:[0,1]
	s_waitcnt lgkmcnt(1)
	v_pk_mul_f32 v[8:9], v[12:13], v[8:9] op_sel_hi:[0,1]
	s_waitcnt lgkmcnt(0)
	v_pk_mul_f32 v[10:11], v[12:13], v[10:11] op_sel_hi:[0,1]
	v_lshlrev_b32_e32 v30, 4, v27
	v_cvt_pk_bf16_f32 v2, v2, v3
	v_cvt_pk_bf16_f32 v3, v4, v5
	v_cvt_pk_bf16_f32 v4, v8, v9
	v_cvt_pk_bf16_f32 v5, v10, v11
	v_add_u32_e32 v8, 0x4000, v30
	s_mov_b64 s[14:15], exec
.LBB0_387:
	v_readfirstlane_b32 s8, v94
	v_readfirstlane_b32 s9, v95
	v_readfirstlane_b32 s10, v174
	v_readfirstlane_b32 s11, v175
	s_nop 4
	s_nop 0
	s_nop 0
	s_nop 0
	s_nop 0
	s_mov_b64 s[0:1], exec
	buffer_store_dwordx4 v[2:5], v8, s[8:11], 0 offen sc1
	s_xor_b64 exec, exec, s[0:1]
	s_cbranch_execnz .LBB0_387
	s_mov_b64 exec, s[14:15]
	v_add_u32_e32 v32, 0x200, v156
	v_lshrrev_b32_e32 v2, 4, v32
	s_mov_b32 s0, 0x7fffff0
	v_and_or_b32 v2, v2, s0, v108
	v_lshlrev_b32_e32 v2, 2, v2
	v_add_u32_e32 v3, s17, v2
	ds_read_b32 v4, v3
	v_add_u32_e32 v3, s16, v2
	v_add3_u32 v7, 0, v2, v7
	ds_read_b32 v12, v3
	ds_read2_b32 v[2:3], v7 offset1:68
	v_add_u32_e32 v8, 0x1000, v7
	s_waitcnt lgkmcnt(2)
	v_mul_f32_e32 v4, 0x3fb8aa3b, v4
	v_exp_f32_e32 v13, v4
	ds_read2_b32 v[4:5], v7 offset0:136 offset1:204
	v_add_u32_e32 v7, 0x1200, v7
	ds_read2_b32 v[8:9], v8 offset0:64 offset1:132
	ds_read2_b32 v[10:11], v7 offset0:72 offset1:140
	s_waitcnt lgkmcnt(4)
	v_mul_f32_e32 v12, v12, v13
	s_waitcnt lgkmcnt(3)
	v_pk_mul_f32 v[2:3], v[2:3], v[12:13] op_sel_hi:[1,0]
	s_waitcnt lgkmcnt(2)
	v_pk_mul_f32 v[4:5], v[12:13], v[4:5] op_sel_hi:[0,1]
	s_waitcnt lgkmcnt(1)
	v_pk_mul_f32 v[8:9], v[12:13], v[8:9] op_sel_hi:[0,1]
	s_waitcnt lgkmcnt(0)
	v_pk_mul_f32 v[10:11], v[12:13], v[10:11] op_sel_hi:[0,1]
	v_lshlrev_b32_e32 v28, 4, v32
	v_cvt_pk_bf16_f32 v2, v2, v3
	v_cvt_pk_bf16_f32 v3, v4, v5
	v_cvt_pk_bf16_f32 v4, v8, v9
	v_cvt_pk_bf16_f32 v5, v10, v11
	v_add_u32_e32 v7, 0x4000, v28
	s_mov_b64 s[14:15], exec
.LBB0_389:
	v_readfirstlane_b32 s8, v94
	v_readfirstlane_b32 s9, v95
	v_readfirstlane_b32 s10, v174
	v_readfirstlane_b32 s11, v175
	s_nop 4
	s_nop 0
	s_nop 0
	s_nop 0
	s_nop 0
	s_mov_b64 s[0:1], exec
	buffer_store_dwordx4 v[2:5], v7, s[8:11], 0 offen sc1
	s_xor_b64 exec, exec, s[0:1]
	s_cbranch_execnz .LBB0_389
	s_mov_b64 exec, s[14:15]
	v_and_b32_e32 v29, 32, v6
	v_or_b32_e32 v2, v29, v24
	v_lshlrev_b32_e32 v34, 2, v2
	v_add_u32_e32 v2, s17, v34
	ds_read_b128 v[6:9], v2
	v_lshrrev_b32_e32 v3, 3, v22
	s_mov_b32 s0, 0xffffff0
	v_and_or_b32 v3, v3, s0, v108
	s_movk_i32 s0, 0x110
	v_mul_lo_u32 v31, v3, s0
	v_add3_u32 v14, 0, v31, v34
	v_readlane_b32 s0, v254, 8
	ds_read_b128 v[10:13], v14 offset:34816
	s_waitcnt lgkmcnt(1)
	v_sub_f32_e32 v8, v23, v8
	v_add_u32_e32 v2, s0, v34
	ds_read_b128 v[2:5], v2
	ds_read_b128 v[36:39], v14 offset:34880
	v_mul_f32_e32 v8, 0x3fb8aa3b, v8
	v_sub_f32_e32 v6, v23, v6
	v_exp_f32_e32 v20, v8
	v_sub_f32_e32 v8, v23, v9
	v_mul_f32_e32 v6, 0x3fb8aa3b, v6
	v_mul_f32_e32 v8, 0x3fb8aa3b, v8
	v_exp_f32_e32 v16, v6
	v_sub_f32_e32 v6, v23, v7
	v_exp_f32_e32 v21, v8
	v_or_b32_e32 v8, 64, v34
	v_mul_f32_e32 v6, 0x3fb8aa3b, v6
	v_add_u32_e32 v9, s17, v8
	v_exp_f32_e32 v17, v6
	s_waitcnt lgkmcnt(1)
	v_pk_mul_f32 v[6:7], v[12:13], v[4:5]
	v_pk_mul_f32 v[14:15], v[10:11], v[2:3]
	ds_read_b128 v[10:13], v9
	v_pk_mul_f32 v[40:41], v[14:15], v[16:17]
	v_pk_mul_f32 v[42:43], v[6:7], v[20:21]
	v_add_u32_e32 v6, s0, v8
	ds_read_b128 v[6:9], v6
	s_waitcnt lgkmcnt(1)
	v_sub_f32_e32 v10, v23, v10
	v_mul_f32_e32 v10, 0x3fb8aa3b, v10
	v_exp_f32_e32 v14, v10
	v_sub_f32_e32 v10, v23, v11
	v_mul_f32_e32 v10, 0x3fb8aa3b, v10
	v_exp_f32_e32 v15, v10
	v_sub_f32_e32 v10, v23, v12
	v_mul_f32_e32 v10, 0x3fb8aa3b, v10
	v_exp_f32_e32 v18, v10
	v_sub_f32_e32 v10, v23, v13
	v_mul_f32_e32 v10, 0x3fb8aa3b, v10
	v_exp_f32_e32 v19, v10
	s_waitcnt lgkmcnt(0)
	v_pk_mul_f32 v[10:11], v[38:39], v[8:9]
	v_pk_mul_f32 v[12:13], v[36:37], v[6:7]
	v_add_u32_e32 v33, 0x8000, v25
	v_pk_mul_f32 v[12:13], v[12:13], v[14:15]
	v_pk_mul_f32 v[36:37], v[10:11], v[18:19]
	v_cvt_pk_bf16_f32 v10, v40, v41
	v_cvt_pk_bf16_f32 v11, v42, v43
	v_cvt_pk_bf16_f32 v12, v12, v13
	v_cvt_pk_bf16_f32 v13, v36, v37
	s_mov_b64 s[14:15], exec
; __device__ __forceinline__ unsigned pack2(float lo, float hi) { return pg8::cvt_pk_bf16(lo, hi); }
; __device__ void prep_unit(unsigned char* lds, int bh, int n, const bf16_t* pc, const float* scal, const float* convw  , float alog, float dtb, unsigned char* unit, float* egl, unsigned* flag, unsigned fval) {
;     ...
;         for (int it = 0; it < 4; ++it) {
;             const int q = u + 256 * it, f = q >> 6, L = q & 63, mt = f >> 1, ks = f & 1, quad = L >> 4, r = L & 15, kd = 16 * mt + r;
;             float v[8];
; #pragma unroll
;             for (int hh = 0; hh < 2; ++hh) { const int c0 = 32 * ks + 16 * hh + 4 * quad; const f32x4 kk = *(const f32x4*)(kT + kd * 68 + c0), gg = *(const f32x4*)(gc + c0), rr = *(const f32x4*)(rk + c0);
; #pragma unroll
;                 for (int j = 0; j < 4; ++j) v[hh * 4 + j] = kk[j] * rr[j] * __expf(glast - gg[j]); }
;             u32x4 w; w.x = pack2(v[0], v[1]); w.y = pack2(v[2], v[3]); w.z = pack2(v[4], v[5]); w.w = pack2(v[6], v[7]);
;             __builtin_amdgcn_raw_buffer_store_b128(w, ur, 32768 + q * 16, 0, 16);
;         }
; #pragma unroll
;         for (int it = 0; it < 2; ++it) {
;             const int q = u + 256 * it, f = q >> 6, L = q & 63, mt = f >> 1, ks = f & 1, quad = L >> 4, r = L & 15, i_ = 16 * mt + r;
;             const f32x4 a0 = *(const f32x4*)(At + i_ * 68 + 32 * ks + 4 * quad), a1 = *(const f32x4*)(At + i_ * 68 + 32 * ks + 16 + 4 * quad);
;             u32x4 w; w.x = pack2(a0[0], a0[1]); w.y = pack2(a0[2], a0[3]); w.z = pack2(a1[0], a1[1]); w.w = pack2(a1[2], a1[3]);
;             __builtin_amdgcn_raw_buffer_store_b128(w, ur, 49152 + q * 16, 0, 16);
;         }
;         if (u == 0) __hip_atomic_store(egl + bh * 128 + n, __expf(glast), __ATOMIC_RELAXED, __HIP_MEMORY_SCOPE_AGENT);
.LBB0_391:
	v_readfirstlane_b32 s8, v94
	v_readfirstlane_b32 s9, v95
	v_readfirstlane_b32 s10, v174
	v_readfirstlane_b32 s11, v175
	s_nop 4
	s_nop 0
	s_nop 0
	s_nop 0
	s_nop 0
	s_mov_b64 s[0:1], exec
	buffer_store_dwordx4 v[10:13], v33, s[8:11], 0 offen sc1
	s_xor_b64 exec, exec, s[0:1]
	s_cbranch_execnz .LBB0_391
	s_mov_b64 exec, s[14:15]
	v_lshrrev_b32_e32 v10, 3, v156
	s_mov_b32 s0, 0xffffff0
	v_and_or_b32 v10, v10, s0, v108
	s_movk_i32 s0, 0x110
	v_mul_lo_u32 v33, v10, s0
	v_add3_u32 v35, 0, v33, v34
	ds_read_b128 v[10:13], v35 offset:34816
	ds_read_b128 v[36:39], v35 offset:34880
	v_add_u32_e32 v35, 0x8000, v26
	s_mov_b64 s[14:15], exec
	s_waitcnt lgkmcnt(1)
	v_pk_mul_f32 v[12:13], v[4:5], v[12:13]
	v_pk_mul_f32 v[10:11], v[2:3], v[10:11]
	s_waitcnt lgkmcnt(0)
	v_pk_mul_f32 v[38:39], v[8:9], v[38:39]
	v_pk_mul_f32 v[36:37], v[6:7], v[36:37]
	v_pk_mul_f32 v[10:11], v[16:17], v[10:11]
	v_pk_mul_f32 v[12:13], v[20:21], v[12:13]
	v_pk_mul_f32 v[36:37], v[14:15], v[36:37]
	v_pk_mul_f32 v[38:39], v[18:19], v[38:39]
	v_cvt_pk_bf16_f32 v10, v10, v11
	v_cvt_pk_bf16_f32 v11, v12, v13
	v_cvt_pk_bf16_f32 v12, v36, v37
	v_cvt_pk_bf16_f32 v13, v38, v39
.LBB0_393:
	v_readfirstlane_b32 s8, v94
	v_readfirstlane_b32 s9, v95
	v_readfirstlane_b32 s10, v174
	v_readfirstlane_b32 s11, v175
	s_nop 4
	s_nop 0
	s_nop 0
	s_nop 0
	s_nop 0
	s_mov_b64 s[0:1], exec
	buffer_store_dwordx4 v[10:13], v35, s[8:11], 0 offen sc1
	s_xor_b64 exec, exec, s[0:1]
	s_cbranch_execnz .LBB0_393
	s_mov_b64 exec, s[14:15]
	v_lshrrev_b32_e32 v10, 3, v27
	s_mov_b32 s0, 0xffffff0
	v_and_or_b32 v10, v10, s0, v108
	s_movk_i32 s0, 0x110
	v_mul_lo_u32 v10, v10, s0
	v_add3_u32 v27, 0, v10, v34
	ds_read_b128 v[10:13], v27 offset:34816
	ds_read_b128 v[36:39], v27 offset:34880
	v_add_u32_e32 v27, 0x8000, v30
	s_mov_b64 s[14:15], exec
	s_waitcnt lgkmcnt(1)
	v_pk_mul_f32 v[12:13], v[4:5], v[12:13]
	v_pk_mul_f32 v[10:11], v[2:3], v[10:11]
	s_waitcnt lgkmcnt(0)
	v_pk_mul_f32 v[38:39], v[8:9], v[38:39]
	v_pk_mul_f32 v[36:37], v[6:7], v[36:37]
	v_pk_mul_f32 v[10:11], v[16:17], v[10:11]
	v_pk_mul_f32 v[12:13], v[20:21], v[12:13]
	v_pk_mul_f32 v[36:37], v[14:15], v[36:37]
	v_pk_mul_f32 v[38:39], v[18:19], v[38:39]
	v_cvt_pk_bf16_f32 v10, v10, v11
	v_cvt_pk_bf16_f32 v11, v12, v13
	v_cvt_pk_bf16_f32 v12, v36, v37
	v_cvt_pk_bf16_f32 v13, v38, v39
.LBB0_395:
	v_readfirstlane_b32 s8, v94
	v_readfirstlane_b32 s9, v95
	v_readfirstlane_b32 s10, v174
	v_readfirstlane_b32 s11, v175
	s_nop 4
	s_nop 0
	s_nop 0
	s_nop 0
	s_nop 0
	s_mov_b64 s[0:1], exec
	buffer_store_dwordx4 v[10:13], v27, s[8:11], 0 offen sc1
	s_xor_b64 exec, exec, s[0:1]
	s_cbranch_execnz .LBB0_395
	s_mov_b64 exec, s[14:15]
	v_lshrrev_b32_e32 v10, 3, v32
	s_mov_b32 s0, 0xffffff0
	v_and_or_b32 v10, v10, s0, v108
	s_movk_i32 s0, 0x110
	v_mul_lo_u32 v10, v10, s0
	v_add3_u32 v27, 0, v10, v34
	ds_read_b128 v[10:13], v27 offset:34816
	s_mov_b64 s[14:15], exec
	s_waitcnt lgkmcnt(0)
	v_pk_mul_f32 v[4:5], v[4:5], v[12:13]
	v_pk_mul_f32 v[2:3], v[2:3], v[10:11]
	v_pk_mul_f32 v[12:13], v[20:21], v[4:5]
	v_pk_mul_f32 v[10:11], v[16:17], v[2:3]
	ds_read_b128 v[2:5], v27 offset:34880
	s_waitcnt lgkmcnt(0)
	v_pk_mul_f32 v[4:5], v[8:9], v[4:5]
	v_pk_mul_f32 v[2:3], v[6:7], v[2:3]
	v_pk_mul_f32 v[8:9], v[18:19], v[4:5]
	v_pk_mul_f32 v[6:7], v[14:15], v[2:3]
	v_cvt_pk_bf16_f32 v2, v10, v11
	v_cvt_pk_bf16_f32 v3, v12, v13
	v_cvt_pk_bf16_f32 v4, v6, v7
	v_cvt_pk_bf16_f32 v5, v8, v9
	v_add_u32_e32 v6, 0x8000, v28
.LBB0_397:
	v_readfirstlane_b32 s8, v94
	v_readfirstlane_b32 s9, v95
	v_readfirstlane_b32 s10, v174
	v_readfirstlane_b32 s11, v175
	s_nop 4
	s_nop 0
	s_nop 0
	s_nop 0
	s_nop 0
	s_mov_b64 s[0:1], exec
	buffer_store_dwordx4 v[2:5], v6, s[8:11], 0 offen sc1
	s_xor_b64 exec, exec, s[0:1]
	s_cbranch_execnz .LBB0_397
	s_mov_b64 exec, s[14:15]
	s_add_i32 s0, 0, 0x1dc00
	v_lshl_add_u32 v6, v29, 2, s0
	v_lshlrev_b32_e32 v7, 2, v24
	v_add3_u32 v8, v6, v31, v7
	ds_read_b128 v[2:5], v8
	ds_read_b128 v[8:11], v8 offset:64
	s_mov_b64 s[14:15], exec
	s_waitcnt lgkmcnt(1)
	v_cvt_pk_bf16_f32 v2, v2, v3
	v_cvt_pk_bf16_f32 v3, v4, v5
	s_waitcnt lgkmcnt(0)
	v_cvt_pk_bf16_f32 v4, v8, v9
	v_cvt_pk_bf16_f32 v5, v10, v11
	v_add_u32_e32 v8, 0xc000, v25
.LBB0_399:
	v_readfirstlane_b32 s8, v94
	v_readfirstlane_b32 s9, v95
	v_readfirstlane_b32 s10, v174
	v_readfirstlane_b32 s11, v175
	s_nop 4
	s_nop 0
	s_nop 0
	s_nop 0
	s_nop 0
	s_mov_b64 s[0:1], exec
	buffer_store_dwordx4 v[2:5], v8, s[8:11], 0 offen sc1
	s_xor_b64 exec, exec, s[0:1]
	s_cbranch_execnz .LBB0_399
	s_mov_b64 exec, s[14:15]
	v_add3_u32 v6, v6, v33, v7
	ds_read_b128 v[2:5], v6
	ds_read_b128 v[6:9], v6 offset:64
	s_mov_b64 s[14:15], exec
	s_waitcnt lgkmcnt(1)
	v_cvt_pk_bf16_f32 v2, v2, v3
	v_cvt_pk_bf16_f32 v3, v4, v5
	s_waitcnt lgkmcnt(0)
	v_cvt_pk_bf16_f32 v4, v6, v7
	v_cvt_pk_bf16_f32 v5, v8, v9
	v_add_u32_e32 v6, 0xc000, v26
.LBB0_401:
	v_readfirstlane_b32 s8, v94
	v_readfirstlane_b32 s9, v95
	v_readfirstlane_b32 s10, v174
	v_readfirstlane_b32 s11, v175
	s_nop 4
	s_nop 0
	s_nop 0
	s_nop 0
	s_nop 0
	s_mov_b64 s[0:1], exec
	buffer_store_dwordx4 v[2:5], v6, s[8:11], 0 offen sc1
	s_xor_b64 exec, exec, s[0:1]
	s_cbranch_execnz .LBB0_401
	s_mov_b64 exec, s[14:15]
	v_cmp_eq_u32_e32 vcc, 0, v22
	s_and_b64 exec, exec, vcc
	s_cbranch_execz .LBB0_404
	v_mul_f32_e32 v2, 0x3fb8aa3b, v23
	v_exp_f32_e32 v6, v2
	v_lshlrev_b32_e32 v2, 2, v109
	v_mov_b32_e32 v3, v1
	v_lshl_add_u64 v[2:3], s[54:55], 0, v[2:3]
	v_lshlrev_b32_e32 v4, 2, v0
	v_mov_b32_e32 v5, v1
	v_lshl_add_u64 v[2:3], v[2:3], 0, v[4:5]
	global_store_dword v[2:3], v6, off sc1

; __device__ __forceinline__ unsigned pack2(float lo, float hi) { return pg8::cvt_pk_bf16(lo, hi); }
; __device__ void prep_unit(unsigned char* lds, int bh, int n, const bf16_t* pc, const float* scal, const float* convw  , float alog, float dtb, unsigned char* unit, float* egl, unsigned* flag, unsigned fval) {
;     ...
;         if (wid < 4) {
; #pragma unroll
;             for (int nt = 0; nt < 2; ++nt)
; #pragma unroll
;                 for (int mt = 0; mt < 4; ++mt) { u32x2 w; w.x = pack2(uw[nt][mt][0], uw[nt][mt][1]); w.y = pack2(uw[nt][mt][2], uw[nt][mt][3]);
;                     __builtin_amdgcn_raw_buffer_store_b64(w, ur, 57344 + ((32 * wid + 16 * nt + cl) * 64 + 16 * mt + quad * 4) * 2, 0, 16); }
;         }
.LBB0_424:
	v_readfirstlane_b32 s8, v94
	v_readfirstlane_b32 s9, v95
	v_readfirstlane_b32 s10, v174
	v_readfirstlane_b32 s11, v175
	s_nop 4
	s_nop 0
	s_nop 0
	s_nop 0
	s_nop 0
	s_mov_b64 s[0:1], exec
	buffer_store_dwordx2 v[14:15], v16, s[8:11], 0 offen sc1
	s_xor_b64 exec, exec, s[0:1]
	s_cbranch_execnz .LBB0_424
	s_mov_b64 exec, s[4:5]
	v_cvt_pk_bf16_f32 v14, v70, v71
	v_cvt_pk_bf16_f32 v15, v72, v73
	s_mov_b64 s[4:5], exec
.LBB0_426:
	v_readfirstlane_b32 s8, v94
	v_readfirstlane_b32 s9, v95
	v_readfirstlane_b32 s10, v174
	v_readfirstlane_b32 s11, v175
	s_nop 4
	s_nop 0
	s_nop 0
	s_nop 0
	s_nop 0
	s_mov_b64 s[0:1], exec
	buffer_store_dwordx2 v[14:15], v16, s[8:11], 0 offen offset:32 sc1
	s_xor_b64 exec, exec, s[0:1]
	s_cbranch_execnz .LBB0_426
	s_mov_b64 exec, s[4:5]
	v_cvt_pk_bf16_f32 v14, v66, v67
	v_cvt_pk_bf16_f32 v15, v68, v69
	s_mov_b64 s[4:5], exec
.LBB0_428:
	v_readfirstlane_b32 s8, v94
	v_readfirstlane_b32 s9, v95
	v_readfirstlane_b32 s10, v174
	v_readfirstlane_b32 s11, v175
	s_nop 4
	s_nop 0
	s_nop 0
	s_nop 0
	s_nop 0
	s_mov_b64 s[0:1], exec
	buffer_store_dwordx2 v[14:15], v16, s[8:11], 0 offen offset:64 sc1
	s_xor_b64 exec, exec, s[0:1]
	s_cbranch_execnz .LBB0_428
	s_mov_b64 exec, s[4:5]
	v_cvt_pk_bf16_f32 v14, v78, v79
	v_cvt_pk_bf16_f32 v15, v80, v81
	s_mov_b64 s[4:5], exec
.LBB0_430:
	v_readfirstlane_b32 s8, v94
	v_readfirstlane_b32 s9, v95
	v_readfirstlane_b32 s10, v174
	v_readfirstlane_b32 s11, v175
	s_nop 4
	s_nop 0
	s_nop 0
	s_nop 0
	s_nop 0
	s_mov_b64 s[0:1], exec
	buffer_store_dwordx2 v[14:15], v16, s[8:11], 0 offen offset:96 sc1
	s_xor_b64 exec, exec, s[0:1]
	s_cbranch_execnz .LBB0_430
	s_mov_b64 exec, s[4:5]
	v_cvt_pk_bf16_f32 v14, v34, v35
	v_cvt_pk_bf16_f32 v15, v36, v37
	s_mov_b64 s[4:5], exec
.LBB0_432:
	v_readfirstlane_b32 s8, v94
	v_readfirstlane_b32 s9, v95
	v_readfirstlane_b32 s10, v174
	v_readfirstlane_b32 s11, v175
	s_nop 4
	s_nop 0
	s_nop 0
	s_nop 0
	s_nop 0
	s_mov_b64 s[0:1], exec
	buffer_store_dwordx2 v[14:15], v16, s[8:11], 0 offen offset:2048 sc1
	s_xor_b64 exec, exec, s[0:1]
	s_cbranch_execnz .LBB0_432
	s_mov_b64 exec, s[4:5]
	v_cvt_pk_bf16_f32 v14, v10, v11
	v_cvt_pk_bf16_f32 v15, v12, v13
	s_mov_b64 s[4:5], exec
.LBB0_434:
	v_readfirstlane_b32 s8, v94
	v_readfirstlane_b32 s9, v95
	v_readfirstlane_b32 s10, v174
	v_readfirstlane_b32 s11, v175
	s_nop 4
	s_nop 0
	s_nop 0
	s_nop 0
	s_nop 0
	s_mov_b64 s[0:1], exec
	buffer_store_dwordx2 v[14:15], v16, s[8:11], 0 offen offset:2080 sc1
	s_xor_b64 exec, exec, s[0:1]
	s_cbranch_execnz .LBB0_434
	s_mov_b64 exec, s[4:5]
	v_cvt_pk_bf16_f32 v14, v6, v7
	v_cvt_pk_bf16_f32 v15, v8, v9
	s_mov_b64 s[4:5], exec
.LBB0_436:
	v_readfirstlane_b32 s8, v94
	v_readfirstlane_b32 s9, v95
	v_readfirstlane_b32 s10, v174
	v_readfirstlane_b32 s11, v175
	s_nop 4
	s_nop 0
	s_nop 0
	s_nop 0
	s_nop 0
	s_mov_b64 s[0:1], exec
	buffer_store_dwordx2 v[14:15], v16, s[8:11], 0 offen offset:2112 sc1
	s_xor_b64 exec, exec, s[0:1]
	s_cbranch_execnz .LBB0_436
	s_mov_b64 exec, s[4:5]
	v_cvt_pk_bf16_f32 v14, v2, v3
	v_cvt_pk_bf16_f32 v15, v4, v5
	s_mov_b64 s[4:5], exec
.LBB0_438:
	v_readfirstlane_b32 s8, v94
	v_readfirstlane_b32 s9, v95
	v_readfirstlane_b32 s10, v174
	v_readfirstlane_b32 s11, v175
	s_nop 4
	s_nop 0
	s_nop 0
	s_nop 0
	s_nop 0
	s_mov_b64 s[0:1], exec
	buffer_store_dwordx2 v[14:15], v16, s[8:11], 0 offen offset:2144 sc1
	s_xor_b64 exec, exec, s[0:1]
	s_cbranch_execnz .LBB0_438
	s_mov_b64 exec, s[4:5]

; __device__ void prep_unit(unsigned char* lds, int bh, int n, const bf16_t* pc, const float* scal, const float* convw  , float alog, float dtb, unsigned char* unit, float* egl, unsigned* flag, unsigned fval) {
;     ...
; #pragma unroll
;     for (int it = 0; it < 2; ++it) { const int q = tid + NTHR * it; __builtin_amdgcn_raw_buffer_store_b128(*(const u32x4*)((const unsigned char*)stage + q * 16), ur, q * 16, 0, 16); }
;     handoff_publish_wt(flag, fval);
.LBB0_443:
	v_readfirstlane_b32 s8, v94
	v_readfirstlane_b32 s9, v95
	v_readfirstlane_b32 s10, v174
	v_readfirstlane_b32 s11, v175
	s_nop 4
	s_nop 0
	s_nop 0
	s_nop 0
	s_nop 0
	s_mov_b64 s[0:1], exec
	s_waitcnt lgkmcnt(0)
	buffer_store_dwordx4 v[2:5], v6, s[8:11], 0 offen sc1
	s_xor_b64 exec, exec, s[0:1]
	s_cbranch_execnz .LBB0_443
	s_mov_b64 exec, s[2:3]
	v_add_u32_e32 v6, 0x2000, v6
	v_readlane_b32 s0, v254, 7
	s_mov_b64 s[2:3], exec
	s_nop 0
	v_add_u32_e32 v2, s0, v6
	ds_read_b128 v[2:5], v2
.LBB0_445:
	v_readfirstlane_b32 s8, v94
	v_readfirstlane_b32 s9, v95
	v_readfirstlane_b32 s10, v174
	v_readfirstlane_b32 s11, v175
	s_nop 4
	s_nop 0
	s_nop 0
	s_nop 0
	s_nop 0
	s_mov_b64 s[0:1], exec
	s_waitcnt lgkmcnt(0)
	buffer_store_dwordx4 v[2:5], v6, s[8:11], 0 offen sc1
	s_xor_b64 exec, exec, s[0:1]
	s_cbranch_execnz .LBB0_445
	s_mov_b64 exec, s[2:3]
	v_writelane_b32 v255, 1, 60
	s_mov_b64 s[0:1], exec
	v_readlane_b32 s2, v254, 1
	v_readlane_b32 s3, v254, 2
	s_and_b64 s[2:3], s[0:1], s[2:3]
	v_readlane_b32 s4, v255, 45
	s_xor_b64 s[0:1], s[2:3], s[0:1]
	v_readlane_b32 s5, v255, 46
	s_mov_b64 exec, s[2:3]
	s_cbranch_execz .LBB0_448
	v_readlane_b32 s2, v255, 11
	v_lshlrev_b32_e32 v2, 2, v109
	v_mov_b32_e32 v3, v1
	v_readlane_b32 s3, v255, 12
	v_lshlrev_b32_e32 v0, 2, v0
	s_nop 0
	v_lshl_add_u64 v[2:3], s[2:3], 0, v[2:3]
	v_lshl_add_u64 v[2:3], v[2:3], 0, v[0:1]
	v_mov_b32_e32 v250, v2
	v_mov_b32_e32 v251, v3
